# speedup vs baseline: 1.0073x; 1.0073x over previous
; #define NEG_INF (-__builtin_inff())
; DI int pi_row(int r) { return (r & ~12) | ((r & 4) << 1) | ((r & 8) >> 1); }
; DI void softmax_step(float (&sc)[16], AState& st, const KV& kv) {
;   float mx = NEG_INF;
; #pragma unroll
;   for (int i = 0; i < 16; ++i) mx = fmaxf(mx, sc[i]);
;   mx = fmaxf(mx, __shfl_xor(mx, 32));
;   const float mnew = fmaxf(st.m, mx);
;   const float meff = (mnew == NEG_INF) ? 0.f : mnew;
;   const float alpha = __expf(st.m - meff);
;   float rs = 0.f;
; #pragma unroll
;   for (int i = 0; i < 16; ++i) { sc[i] = __expf(sc[i] - meff); rs += sc[i]; }
;   st.l = st.l * alpha + rs;
;   st.m = mnew;
;   if (__any(alpha != 1.f)) {
; #pragma unroll
;     for (int i = 0; i < 16; ++i) { st.o0[i] *= alpha; st.o1[i] *= alpha; }
; DI void nsa_group(const u16* R, const u16* T, const float* Oc, const float* Ow, const u32* selm, const float* bg, const float* gh, u16* obuf, int qtile, char* lds) {
;     ...
;       if (myh) {
;         const char* b = lds + buf * (2 * NG_TB) + part * NG_TB;
;         const u16* sK = reinterpret_cast<const u16*>(b);
;         const u16* sV = reinterpret_cast<const u16*>(b + 32 * FG_KROW * 2);
;         KV kv;
;         const int prow = pi_row(r);
; #pragma unroll
;         for (int ks = 0; ks < 4; ++ks) kv.k[ks] = ld16(sK + prow * FG_KROW + ks * 16 + h2 * 8);
; #pragma unroll
;         for (int dt = 0; dt < 2; ++dt)
; #pragma unroll
;           for (int a = 0; a < 2; ++a) kv.v[dt * 2 + a] = ld16(sV + (dt * 32 + r) * FG_VROW + a * 16 + h2 * 8);
;         f32x16 s = qk_tile(kv, q);
;         float sc[16];
;         const int nb = myn + 8 * h2;
; #pragma unroll
;         for (int i = 0; i < 16; ++i) {
;           const int n = nb + (i & 7) + 16 * (i >> 3);
;           const int dist = tq - n;
;           sc[i] = (dist >= 0 && mylb) ? s[i] + nslope * (float)dist : NEG_INF;
;         }
;         softmax_step(sc, st, kv);
.LBB0_1189:
	s_or_b64 exec, exec, s[54:55]
	s_or_b64 s[52:53], s[46:47], s[52:53]
	s_andn2_b64 vcc, exec, s[52:53]
	s_cbranch_vccnz .LBB0_1193
	s_and_b64 s[52:53], s[46:47], exec
	s_mul_i32 s14, s11, 0x4c00
	s_cselect_b32 s12, s12, s91
	s_add_i32 s14, s86, s14
	v_add_u32_e32 v0, s14, v111
	v_add_u32_e32 v10, v0, v110
	ds_read_b128 v[2:5], v10
	ds_read_b128 v[6:9], v10 offset:32
	v_cndmask_b32_e64 v11, 0, 1, s[48:49]
	v_cndmask_b32_e64 v12, 0, 1, s[50:51]
	s_waitcnt lgkmcnt(1)
	v_mfma_f32_32x32x16_bf16 v[48:63], v[2:5], v[64:67], 0
	v_cndmask_b32_e64 v2, v12, v11, s[46:47]
	v_and_b32_e32 v2, 1, v2
	v_cmp_eq_u32_e32 vcc, 1, v2
	ds_read_b128 v[2:5], v10 offset:64
	v_add_u32_e32 v11, s12, v112
	v_sub_u32_e32 v12, v88, v11
	v_xad_u32 v13, v11, -1, v88
	s_waitcnt lgkmcnt(1)
	v_mfma_f32_32x32x16_bf16 v[48:63], v[6:9], v[68:71], v[48:63]
	ds_read_b128 v[6:9], v10 offset:96
	v_cvt_f32_u32_e32 v10, v12
	v_sub_u32_e32 v14, v114, v11
	v_sub_u32_e32 v15, v115, v11
	v_cmp_lt_i32_e64 s[48:49], -1, v12
	v_cmp_lt_i32_e64 s[50:51], -1, v13
	s_and_b64 s[48:49], s[48:49], vcc
	s_waitcnt lgkmcnt(1)
	v_mfma_f32_32x32x16_bf16 v[48:63], v[2:5], v[72:75], v[48:63]
	v_cvt_f32_u32_e32 v2, v13
	v_cvt_f32_u32_e32 v3, v14
	v_cvt_f32_u32_e32 v4, v15
	v_sub_u32_e32 v129, v116, v11
	v_cmp_lt_i32_e64 s[52:53], -1, v14
	v_cmp_lt_i32_e64 s[54:55], -1, v15
	v_cvt_f32_u32_e32 v5, v129
	s_waitcnt lgkmcnt(0)
	v_mfma_f32_32x32x16_bf16 v[48:63], v[6:9], v[76:79], v[48:63]
	v_cmp_lt_i32_e64 s[56:57], -1, v129
	s_nop 10
	v_fma_f32 v6, -v109, v10, v48
	v_fma_f32 v2, -v109, v2, v49
	v_cndmask_b32_e64 v130, v184, v6, s[48:49]
	s_and_b64 s[48:49], s[50:51], vcc
	v_fma_f32 v3, -v109, v3, v50
	v_cndmask_b32_e64 v15, v184, v2, s[48:49]
	s_and_b64 s[48:49], s[52:53], vcc
	v_fma_f32 v4, -v109, v4, v51
	v_cndmask_b32_e64 v14, v184, v3, s[48:49]
	s_and_b64 s[48:49], s[54:55], vcc
	v_sub_u32_e32 v3, v117, v11
	v_cndmask_b32_e64 v131, v184, v4, s[48:49]
	v_cvt_f32_u32_e32 v4, v3
	v_fma_f32 v2, -v109, v5, v52
	s_and_b64 s[48:49], s[56:57], vcc
	v_cndmask_b32_e64 v52, v184, v2, s[48:49]
	v_cmp_lt_i32_e64 s[48:49], -1, v3
	v_sub_u32_e32 v3, v118, v11
	v_fma_f32 v2, -v109, v4, v53
	v_cvt_f32_u32_e32 v4, v3
	s_and_b64 s[48:49], s[48:49], vcc
	v_cndmask_b32_e64 v53, v184, v2, s[48:49]
	v_cmp_lt_i32_e64 s[48:49], -1, v3
	v_sub_u32_e32 v3, v119, v11
	v_fma_f32 v2, -v109, v4, v54
	v_cvt_f32_u32_e32 v4, v3
	s_and_b64 s[48:49], s[48:49], vcc
	v_cndmask_b32_e64 v54, v184, v2, s[48:49]
	v_cmp_lt_i32_e64 s[48:49], -1, v3
	v_sub_u32_e32 v3, v120, v11
	v_fma_f32 v2, -v109, v4, v55
	v_cvt_f32_u32_e32 v4, v3
	s_and_b64 s[48:49], s[48:49], vcc
	v_cndmask_b32_e64 v55, v184, v2, s[48:49]
	v_cmp_lt_i32_e64 s[48:49], -1, v3
	v_sub_u32_e32 v3, v121, v11
	v_fma_f32 v2, -v109, v4, v56
	v_cvt_f32_u32_e32 v4, v3
	s_and_b64 s[48:49], s[48:49], vcc
	v_cndmask_b32_e64 v56, v184, v2, s[48:49]
	v_cmp_lt_i32_e64 s[48:49], -1, v3
	v_sub_u32_e32 v3, v122, v11
	v_fma_f32 v2, -v109, v4, v57
	v_cvt_f32_u32_e32 v4, v3
	s_and_b64 s[48:49], s[48:49], vcc
	v_cndmask_b32_e64 v57, v184, v2, s[48:49]
	v_cmp_lt_i32_e64 s[48:49], -1, v3
	v_sub_u32_e32 v3, v123, v11
	v_fma_f32 v2, -v109, v4, v58
	v_cvt_f32_u32_e32 v4, v3
	s_and_b64 s[48:49], s[48:49], vcc
	v_cndmask_b32_e64 v132, v184, v2, s[48:49]
	v_cmp_lt_i32_e64 s[48:49], -1, v3
	v_sub_u32_e32 v3, v124, v11
	v_fma_f32 v2, -v109, v4, v59
	v_cvt_f32_u32_e32 v4, v3
	s_and_b64 s[48:49], s[48:49], vcc
	v_cndmask_b32_e64 v59, v184, v2, s[48:49]
	v_cmp_lt_i32_e64 s[48:49], -1, v3
	v_sub_u32_e32 v3, v125, v11
	v_fma_f32 v2, -v109, v4, v60
	v_cvt_f32_u32_e32 v4, v3
	s_and_b64 s[48:49], s[48:49], vcc
	v_cndmask_b32_e64 v60, v184, v2, s[48:49]
	v_cmp_lt_i32_e64 s[48:49], -1, v3
	v_sub_u32_e32 v3, v126, v11
	v_fma_f32 v2, -v109, v4, v61
	v_cvt_f32_u32_e32 v4, v3
	s_and_b64 s[48:49], s[48:49], vcc
	v_cndmask_b32_e64 v133, v184, v2, s[48:49]
	v_cmp_lt_i32_e64 s[48:49], -1, v3
	v_sub_u32_e32 v3, v127, v11
	v_fma_f32 v2, -v109, v4, v62
	v_cvt_f32_u32_e32 v4, v3
	s_and_b64 s[48:49], s[48:49], vcc
	v_cndmask_b32_e64 v62, v184, v2, s[48:49]
	v_cmp_lt_i32_e64 s[48:49], -1, v3
	v_fma_f32 v2, -v109, v4, v63
	s_and_b64 vcc, s[48:49], vcc
	v_cndmask_b32_e32 v58, v184, v2, vcc
	v_max3_f32 v2, v130, s35, v15
	v_max3_f32 v2, v2, v14, v131
	v_max3_f32 v2, v2, v52, v53
	v_max3_f32 v2, v2, v54, v55
	v_max3_f32 v2, v2, v56, v57
	v_max3_f32 v2, v2, v132, v59
	v_max3_f32 v2, v2, v60, v133
	v_max3_f32 v2, v2, v62, v58
	ds_bpermute_b32 v3, v138, v2
	v_add_u32_e32 v4, v0, v113
	ds_read_b128 v[48:51], v4 offset:4608
	ds_read_b128 v[10:13], v4 offset:4640
	s_waitcnt lgkmcnt(2)
	v_max3_f32 v129, v128, v2, v3
	v_cmp_neq_f32_e32 vcc, s35, v129
	ds_read_b128 v[6:9], v4 offset:7168
	ds_read_b128 v[2:5], v4 offset:7200
	v_cndmask_b32_e32 v61, 0, v129, vcc
	v_sub_f32_e32 v0, v128, v61
	v_mul_f32_e32 v0, 0x3fb8aa3b, v0
	v_exp_f32_e32 v0, v0
	s_nop 0
	v_cmp_neq_f32_e32 vcc, 1.0, v0
	s_cbranch_vccz .LBB0_1192
	v_mul_f32_e32 v46, v46, v0
	v_mul_f32_e32 v47, v47, v0
	v_mul_f32_e32 v44, v44, v0
	v_mul_f32_e32 v45, v45, v0
	v_mul_f32_e32 v42, v42, v0
	v_mul_f32_e32 v43, v43, v0
	v_mul_f32_e32 v40, v40, v0
	v_mul_f32_e32 v41, v41, v0
	v_mul_f32_e32 v38, v38, v0
	v_mul_f32_e32 v39, v39, v0
	v_mul_f32_e32 v36, v36, v0
	v_mul_f32_e32 v37, v37, v0
	v_mul_f32_e32 v34, v34, v0
	v_mul_f32_e32 v35, v35, v0
	v_mul_f32_e32 v32, v32, v0
	v_mul_f32_e32 v33, v33, v0
	v_mul_f32_e32 v30, v30, v0
	v_mul_f32_e32 v31, v31, v0
	v_mul_f32_e32 v28, v28, v0
	v_mul_f32_e32 v29, v29, v0
	v_mul_f32_e32 v26, v26, v0
	v_mul_f32_e32 v27, v27, v0
	v_mul_f32_e32 v24, v24, v0
	v_mul_f32_e32 v25, v25, v0
	v_mul_f32_e32 v22, v22, v0
	v_mul_f32_e32 v23, v23, v0
	v_mul_f32_e32 v20, v20, v0
	v_mul_f32_e32 v21, v21, v0
	v_mul_f32_e32 v18, v18, v0
	v_mul_f32_e32 v19, v19, v0
	v_mul_f32_e32 v16, v16, v0
	v_mul_f32_e32 v17, v17, v0
